# grid barrier: non-leader workgroups wait on the global release word instead of the per-XCD word (one device-scope hop less)
# speedup vs baseline: 1.0479x; 1.0068x over previous
; __device__ __forceinline__ unsigned xb_ld(unsigned* p)              { return __hip_atomic_load(p, __ATOMIC_RELAXED, __HIP_MEMORY_SCOPE_AGENT); }
; __device__ __forceinline__ unsigned xb_add(unsigned* p, unsigned v) { return __hip_atomic_fetch_add(p, v, __ATOMIC_RELAXED, __HIP_MEMORY_SCOPE_AGENT); }
; #define XB_SPIN(cond, bar) do { unsigned _sp = 0; while (cond) { __builtin_amdgcn_s_sleep(1); \
;     if ((++_sp & 255u) == 0u) { if (xb_ld(&(bar)[XB_TMO])) break; if (_sp > XB_SPIN_CAP) { atomicAdd(&(bar)[XB_TMO], 1u); break; } } } } while (0)
; __device__ __forceinline__ void xcd_barrier(const XcdBarrier& b) {
;     ...
;         const unsigned old = xb_add(&bar[XB_XSUB(b.x)], 1u);
;         const unsigned gen = old / nloc;
;         if (old + 1u == (gen + 1u) * nloc) {
;             __builtin_amdgcn_fence(__ATOMIC_RELEASE, "agent");
;             asm volatile("s_waitcnt vmcnt(0)" ::: "memory");
;             const unsigned og = xb_add(&bar[XB_TOP], 1u);
;             const unsigned tg = og / nx;
;             if (og + 1u == (tg + 1u) * nx) xb_add(&bar[XB_TOPGEN], 1u);
;             else XB_SPIN(xb_ld(&bar[XB_TOPGEN]) == tg, bar);
;             __builtin_amdgcn_fence(__ATOMIC_ACQUIRE, "agent");
;             xb_add(&bar[XB_XGEN(b.x)], 1u);
;             asm volatile("s_waitcnt vmcnt(0)" ::: "memory");
;         } else {
;             XB_SPIN(xb_ld(&bar[XB_XGEN(b.x)]) == gen, bar);
;             __builtin_amdgcn_fence(__ATOMIC_ACQUIRE, "agent");
;             asm volatile("s_waitcnt vmcnt(0)" ::: "memory");
;         }
.LBB0_146:
	s_or_b64 exec, exec, s[6:7]
	v_cvt_f32_u32_e32 v4, v2
	s_waitcnt vmcnt(0)
	v_readfirstlane_b32 s4, v3
	v_sub_u32_e32 v3, 0, v2
	v_rcp_iflag_f32_e32 v4, v4
	v_add_u32_e32 v5, s4, v1
	v_mul_f32_e32 v4, 0x4f7ffffe, v4
	v_cvt_u32_f32_e32 v4, v4
	v_mul_lo_u32 v1, v3, v4
	v_mul_hi_u32 v1, v4, v1
	v_add_u32_e32 v1, v4, v1
	v_mul_hi_u32 v1, v5, v1
	v_mul_lo_u32 v3, v1, v2
	v_sub_u32_e32 v3, v5, v3
	v_add_u32_e32 v4, 1, v1
	v_cmp_ge_u32_e32 vcc, v3, v2
	s_nop 1
	v_cndmask_b32_e32 v1, v1, v4, vcc
	v_sub_u32_e32 v4, v3, v2
	v_cndmask_b32_e32 v3, v3, v4, vcc
	v_add_u32_e32 v4, 1, v1
	v_cmp_ge_u32_e32 vcc, v3, v2
	v_add_u32_e32 v3, 1, v5
	s_nop 0
	v_cndmask_b32_e32 v1, v1, v4, vcc
	v_mul_lo_u32 v4, v2, v1
	v_add_u32_e32 v2, v4, v2
	v_cmp_ne_u32_e32 vcc, v3, v2
	s_and_saveexec_b64 s[4:5], vcc
	s_xor_b64 s[4:5], exec, s[4:5]
	s_cbranch_execz .LBB0_160
	s_waitcnt lgkmcnt(0)
	v_readlane_b32 s10, v254, 8
	v_readlane_b32 s11, v254, 9
	v_mov_b32_e32 v0, 0
	s_add_u32 s10, s10, 0xfa03500
	s_addc_u32 s11, s11, 0
	global_load_dword v0, v0, s[10:11] sc1
	s_waitcnt vmcnt(0)
	v_cmp_eq_u32_e32 vcc, v0, v1
	s_and_saveexec_b64 s[6:7], vcc
	s_cbranch_execz .LBB0_159
	v_readlane_b32 s8, v254, 8
	v_readlane_b32 s9, v254, 9
	s_add_u32 s8, s8, 0xfa00200
	s_addc_u32 s9, s9, 0
	s_mov_b32 s22, 1
	s_mov_b64 s[12:13], 0
	v_mov_b32_e32 v0, 0
	s_branch .LBB0_150

; __device__ __forceinline__ unsigned xb_ld(unsigned* p)              { return __hip_atomic_load(p, __ATOMIC_RELAXED, __HIP_MEMORY_SCOPE_AGENT); }
; __device__ __forceinline__ unsigned xb_add(unsigned* p, unsigned v) { return __hip_atomic_fetch_add(p, v, __ATOMIC_RELAXED, __HIP_MEMORY_SCOPE_AGENT); }
; #define XB_SPIN(cond, bar) do { unsigned _sp = 0; while (cond) { __builtin_amdgcn_s_sleep(1); \
;     if ((++_sp & 255u) == 0u) { if (xb_ld(&(bar)[XB_TMO])) break; if (_sp > XB_SPIN_CAP) { atomicAdd(&(bar)[XB_TMO], 1u); break; } } } } while (0)
; __device__ __forceinline__ void xcd_barrier(const XcdBarrier& b) {
;     ...
;         const unsigned old = xb_add(&bar[XB_XSUB(b.x)], 1u);
;         const unsigned gen = old / nloc;
;         if (old + 1u == (gen + 1u) * nloc) {
;             __builtin_amdgcn_fence(__ATOMIC_RELEASE, "agent");
;             asm volatile("s_waitcnt vmcnt(0)" ::: "memory");
;             const unsigned og = xb_add(&bar[XB_TOP], 1u);
;             const unsigned tg = og / nx;
;             if (og + 1u == (tg + 1u) * nx) xb_add(&bar[XB_TOPGEN], 1u);
;             else XB_SPIN(xb_ld(&bar[XB_TOPGEN]) == tg, bar);
;             __builtin_amdgcn_fence(__ATOMIC_ACQUIRE, "agent");
;             xb_add(&bar[XB_XGEN(b.x)], 1u);
;             asm volatile("s_waitcnt vmcnt(0)" ::: "memory");
;         } else {
;             XB_SPIN(xb_ld(&bar[XB_XGEN(b.x)]) == gen, bar);
;             __builtin_amdgcn_fence(__ATOMIC_ACQUIRE, "agent");
;             asm volatile("s_waitcnt vmcnt(0)" ::: "memory");
;         }
.LBB0_2294:
	s_or_b64 exec, exec, s[8:9]
	v_cvt_f32_u32_e32 v4, v2
	s_waitcnt vmcnt(0)
	v_readfirstlane_b32 s6, v3
	v_sub_u32_e32 v3, 0, v2
	v_rcp_iflag_f32_e32 v4, v4
	v_add_u32_e32 v5, s6, v1
	v_mul_f32_e32 v4, 0x4f7ffffe, v4
	v_cvt_u32_f32_e32 v4, v4
	v_mul_lo_u32 v1, v3, v4
	v_mul_hi_u32 v1, v4, v1
	v_add_u32_e32 v1, v4, v1
	v_mul_hi_u32 v1, v5, v1
	v_mul_lo_u32 v3, v1, v2
	v_sub_u32_e32 v3, v5, v3
	v_add_u32_e32 v4, 1, v1
	v_cmp_ge_u32_e32 vcc, v3, v2
	s_nop 1
	v_cndmask_b32_e32 v1, v1, v4, vcc
	v_sub_u32_e32 v4, v3, v2
	v_cndmask_b32_e32 v3, v3, v4, vcc
	v_add_u32_e32 v4, 1, v1
	v_cmp_ge_u32_e32 vcc, v3, v2
	v_add_u32_e32 v3, 1, v5
	s_nop 0
	v_cndmask_b32_e32 v1, v1, v4, vcc
	v_mul_lo_u32 v4, v2, v1
	v_add_u32_e32 v2, v4, v2
	v_cmp_ne_u32_e32 vcc, v3, v2
	s_and_saveexec_b64 s[6:7], vcc
	s_xor_b64 s[6:7], exec, s[6:7]
	s_cbranch_execz .LBB0_2308
	s_waitcnt lgkmcnt(0)
	v_readlane_b32 s12, v254, 8
	v_readlane_b32 s13, v254, 9
	v_mov_b32_e32 v0, 0
	s_add_u32 s12, s12, 0xfa03500
	s_addc_u32 s13, s13, 0
	global_load_dword v0, v0, s[12:13] sc1
	s_waitcnt vmcnt(0)
	v_cmp_eq_u32_e32 vcc, v0, v1
	s_and_saveexec_b64 s[8:9], vcc
	s_cbranch_execz .LBB0_2307
	v_readlane_b32 s10, v254, 8
	v_readlane_b32 s11, v254, 9
	s_add_u32 s10, s10, 0xfa00200
	s_addc_u32 s11, s11, 0
	s_mov_b32 s24, 1
	s_mov_b64 s[14:15], 0
	v_mov_b32_e32 v0, 0
	s_branch .LBB0_2298

; __device__ __forceinline__ unsigned xb_add(unsigned* p, unsigned v) { return __hip_atomic_fetch_add(p, v, __ATOMIC_RELAXED, __HIP_MEMORY_SCOPE_AGENT); }
; __device__ __forceinline__ void xcd_barrier(const XcdBarrier& b) {
;     ...
;             __builtin_amdgcn_fence(__ATOMIC_ACQUIRE, "agent");
;             xb_add(&bar[XB_XGEN(b.x)], 1u);
;             asm volatile("s_waitcnt vmcnt(0)" ::: "memory");
.LBB0_2573:
	s_or_b64 exec, exec, s[6:7]
	s_mov_b64 s[6:7], exec
	v_mbcnt_lo_u32_b32 v0, s6, 0
	v_mbcnt_hi_u32_b32 v0, s7, v0
	v_cmp_eq_u32_e32 vcc, 0, v0
	s_waitcnt vmcnt(0)
	buffer_inv sc1
	s_and_saveexec_b64 s[8:9], vcc
	s_cbranch_execz .LBB0_2575
	s_bcnt1_i32_b64 s6, s[6:7]
	v_mov_b32_e32 v0, 0x2000
	v_mov_b32_e32 v1, s6
	global_atomic_add v0, v1, s[2:3] offset:1024
	s_nop 0
	s_nop 0
	s_nop 0
	s_nop 0
	s_nop 0
	s_nop 0
	s_nop 0
	s_nop 0
	s_nop 0
	s_nop 0
	s_nop 0
	s_nop 0
	s_nop 0
	s_nop 0
	s_nop 0
	s_nop 0
	s_nop 0
	s_nop 0
	s_nop 0
	s_nop 0
	s_nop 0
	s_nop 0
	s_nop 0
	s_nop 0
	s_nop 0
	s_nop 0
	s_nop 0
	s_nop 0
	s_nop 0
	s_nop 0
	s_nop 0
	s_nop 0
	s_nop 0
	s_nop 0
	s_nop 0
